# v51 + sel score loops: weighted relu head-sum with packed f32 (pk_mul + 3 pk_fma + add per 8-head pair instead of 2 fma + 6 fmac + add; f32, summation order only)
# baseline (speedup 1.0000x reference)
.LBB0_820:
	s_add_i32 s40, s8, -3
	s_min_i32 s9, s40, s7
	s_lshl_b32 s98, s9, 15
	s_waitcnt vmcnt(12)
	v_lshl_add_u64 v[60:61], v[244:245], 0, s[98:99]
	global_load_dwordx4 v[88:91], v[60:61], off
	global_load_dwordx4 v[92:95], v[60:61], off offset:1024
	global_load_dwordx4 v[56:59], v[60:61], off offset:2048
	s_nop 0
	global_load_dwordx4 v[60:63], v[60:61], off offset:3072
	v_add_u32_e32 v103, v178, v98
	s_waitcnt vmcnt(15)
	ds_write_b128 v103, v[64:67]
	s_waitcnt vmcnt(14)
	ds_write_b128 v103, v[68:71] offset:1152
	v_add_u32_e32 v107, v179, v96
	ds_read_b128 v[64:67], v107
	ds_read_b128 v[68:71], v107 offset:64
	s_waitcnt vmcnt(13)
	ds_write_b128 v103, v[32:35]
	s_waitcnt vmcnt(12)
	ds_write_b128 v103, v[36:39] offset:1152
	ds_read_b128 v[32:35], v107
	ds_read_b128 v[36:39], v107 offset:64
	s_waitcnt lgkmcnt(4)
	v_mfma_f32_16x16x32_bf16 v[208:211], v[0:3], v[64:67], 0
	v_mfma_f32_16x16x32_bf16 v[212:215], v[8:11], v[64:67], 0
	v_mfma_f32_16x16x32_bf16 v[216:219], v[16:19], v[64:67], 0
	v_mfma_f32_16x16x32_bf16 v[220:223], v[24:27], v[64:67], 0
	v_mfma_f32_16x16x32_bf16 v[208:211], v[4:7], v[68:71], v[208:211]
	v_mfma_f32_16x16x32_bf16 v[212:215], v[12:15], v[68:71], v[212:215]
	v_mfma_f32_16x16x32_bf16 v[216:219], v[20:23], v[68:71], v[216:219]
	v_mfma_f32_16x16x32_bf16 v[220:223], v[28:31], v[68:71], v[220:223]
	s_waitcnt lgkmcnt(0)
	v_mfma_f32_16x16x32_bf16 v[224:227], v[0:3], v[32:35], 0
	v_mfma_f32_16x16x32_bf16 v[228:231], v[8:11], v[32:35], 0
	v_mfma_f32_16x16x32_bf16 v[232:235], v[16:19], v[32:35], 0
	v_mfma_f32_16x16x32_bf16 v[236:239], v[24:27], v[32:35], 0
	v_max_f32_e32 v208, 0, v208
	v_max_f32_e32 v209, 0, v209
	v_pk_mul_f32 v[208:209], v[208:209], v[162:163]
	v_max_f32_e32 v210, 0, v210
	v_max_f32_e32 v211, 0, v211
	v_pk_fma_f32 v[208:209], v[210:211], v[164:165], v[208:209]
	v_mfma_f32_16x16x32_bf16 v[224:227], v[4:7], v[36:39], v[224:227]
	v_max_f32_e32 v212, 0, v212
	v_max_f32_e32 v213, 0, v213
	v_pk_fma_f32 v[208:209], v[212:213], v[166:167], v[208:209]
	v_max_f32_e32 v214, 0, v214
	v_max_f32_e32 v215, 0, v215
	v_pk_fma_f32 v[208:209], v[214:215], v[168:169], v[208:209]
	v_mfma_f32_16x16x32_bf16 v[228:231], v[12:15], v[36:39], v[228:231]
	v_add_f32_e32 v208, v208, v209
	ds_write_b32 v99, v208
	v_max_f32_e32 v216, 0, v216
	v_max_f32_e32 v217, 0, v217
	v_pk_mul_f32 v[216:217], v[216:217], v[170:171]
	v_max_f32_e32 v218, 0, v218
	v_max_f32_e32 v219, 0, v219
	v_mfma_f32_16x16x32_bf16 v[232:235], v[20:23], v[36:39], v[232:235]
	v_pk_fma_f32 v[216:217], v[218:219], v[172:173], v[216:217]
	v_max_f32_e32 v220, 0, v220
	v_max_f32_e32 v221, 0, v221
	v_pk_fma_f32 v[216:217], v[220:221], v[174:175], v[216:217]
	v_max_f32_e32 v222, 0, v222
	v_max_f32_e32 v223, 0, v223
	v_mfma_f32_16x16x32_bf16 v[236:239], v[28:31], v[36:39], v[236:239]
	v_pk_fma_f32 v[216:217], v[222:223], v[176:177], v[216:217]
	v_add_f32_e32 v216, v216, v217
	ds_write_b32 v246, v216
	v_max_f32_e32 v224, 0, v224
	v_max_f32_e32 v225, 0, v225
	v_pk_mul_f32 v[224:225], v[224:225], v[162:163]
	v_max_f32_e32 v226, 0, v226
	v_max_f32_e32 v227, 0, v227
	v_pk_fma_f32 v[224:225], v[226:227], v[164:165], v[224:225]
	v_max_f32_e32 v228, 0, v228
	v_max_f32_e32 v229, 0, v229
	v_pk_fma_f32 v[224:225], v[228:229], v[166:167], v[224:225]
	v_max_f32_e32 v230, 0, v230
	v_max_f32_e32 v231, 0, v231
	v_pk_fma_f32 v[224:225], v[230:231], v[168:169], v[224:225]
	v_add_f32_e32 v224, v224, v225
	ds_write_b32 v99, v224 offset:64
	v_max_f32_e32 v232, 0, v232
	v_max_f32_e32 v233, 0, v233
	v_pk_mul_f32 v[232:233], v[232:233], v[170:171]
	v_max_f32_e32 v234, 0, v234
	v_max_f32_e32 v235, 0, v235
	v_pk_fma_f32 v[232:233], v[234:235], v[172:173], v[232:233]
	v_max_f32_e32 v236, 0, v236
	v_max_f32_e32 v237, 0, v237
	v_pk_fma_f32 v[232:233], v[236:237], v[174:175], v[232:233]
	v_max_f32_e32 v238, 0, v238
	v_max_f32_e32 v239, 0, v239
	v_pk_fma_f32 v[232:233], v[238:239], v[176:177], v[232:233]
	v_add_f32_e32 v232, v232, v233
	ds_write_b32 v246, v232 offset:64
	s_add_i32 s9, s8, -2
	s_min_i32 s57, s9, s7
	s_lshl_b32 s98, s57, 15
	v_lshl_add_u64 v[36:37], v[244:245], 0, s[98:99]
	global_load_dwordx4 v[64:67], v[36:37], off
	global_load_dwordx4 v[68:71], v[36:37], off offset:1024
	global_load_dwordx4 v[32:35], v[36:37], off offset:2048
	s_nop 0
	global_load_dwordx4 v[36:39], v[36:37], off offset:3072
	s_add_i32 s57, s8, -5
	s_cmp_ge_i32 s57, s6
	s_cbranch_scc1 .LBB0_822
	s_waitcnt vmcnt(15)
	ds_write_b128 v103, v[72:75]
	s_waitcnt vmcnt(14)
	ds_write_b128 v103, v[76:79] offset:1152
	ds_read_b128 v[72:75], v107
	ds_read_b128 v[76:79], v107 offset:64
	s_waitcnt vmcnt(13)
	ds_write_b128 v103, v[40:43]
	s_waitcnt vmcnt(12)
	ds_write_b128 v103, v[44:47] offset:1152
	ds_read_b128 v[40:43], v107
	ds_read_b128 v[44:47], v107 offset:64
	s_waitcnt lgkmcnt(4)
	v_mfma_f32_16x16x32_bf16 v[208:211], v[0:3], v[72:75], 0
	v_mfma_f32_16x16x32_bf16 v[212:215], v[8:11], v[72:75], 0
	v_mfma_f32_16x16x32_bf16 v[216:219], v[16:19], v[72:75], 0
	v_mfma_f32_16x16x32_bf16 v[220:223], v[24:27], v[72:75], 0
	v_mfma_f32_16x16x32_bf16 v[208:211], v[4:7], v[76:79], v[208:211]
	v_mfma_f32_16x16x32_bf16 v[212:215], v[12:15], v[76:79], v[212:215]
	v_mfma_f32_16x16x32_bf16 v[216:219], v[20:23], v[76:79], v[216:219]
	v_mfma_f32_16x16x32_bf16 v[220:223], v[28:31], v[76:79], v[220:223]
	s_waitcnt lgkmcnt(0)
	v_mfma_f32_16x16x32_bf16 v[224:227], v[0:3], v[40:43], 0
	v_mfma_f32_16x16x32_bf16 v[228:231], v[8:11], v[40:43], 0
	v_mfma_f32_16x16x32_bf16 v[232:235], v[16:19], v[40:43], 0
	v_mfma_f32_16x16x32_bf16 v[236:239], v[24:27], v[40:43], 0
	v_max_f32_e32 v208, 0, v208
	v_max_f32_e32 v209, 0, v209
	v_pk_mul_f32 v[208:209], v[208:209], v[162:163]
	v_max_f32_e32 v210, 0, v210
	v_max_f32_e32 v211, 0, v211
	v_pk_fma_f32 v[208:209], v[210:211], v[164:165], v[208:209]
	v_mfma_f32_16x16x32_bf16 v[224:227], v[4:7], v[44:47], v[224:227]
	v_max_f32_e32 v212, 0, v212
	v_max_f32_e32 v213, 0, v213
	v_pk_fma_f32 v[208:209], v[212:213], v[166:167], v[208:209]
	v_max_f32_e32 v214, 0, v214
	v_max_f32_e32 v215, 0, v215
	v_pk_fma_f32 v[208:209], v[214:215], v[168:169], v[208:209]
	v_mfma_f32_16x16x32_bf16 v[228:231], v[12:15], v[44:47], v[228:231]
	v_add_f32_e32 v208, v208, v209
	ds_write_b32 v99, v208 offset:1024
	v_max_f32_e32 v216, 0, v216
	v_max_f32_e32 v217, 0, v217
	v_pk_mul_f32 v[216:217], v[216:217], v[170:171]
	v_max_f32_e32 v218, 0, v218
	v_max_f32_e32 v219, 0, v219
	v_mfma_f32_16x16x32_bf16 v[232:235], v[20:23], v[44:47], v[232:235]
	v_pk_fma_f32 v[216:217], v[218:219], v[172:173], v[216:217]
	v_max_f32_e32 v220, 0, v220
	v_max_f32_e32 v221, 0, v221
	v_pk_fma_f32 v[216:217], v[220:221], v[174:175], v[216:217]
	v_max_f32_e32 v222, 0, v222
	v_max_f32_e32 v223, 0, v223
	v_mfma_f32_16x16x32_bf16 v[236:239], v[28:31], v[44:47], v[236:239]
	v_pk_fma_f32 v[216:217], v[222:223], v[176:177], v[216:217]
	v_add_f32_e32 v216, v216, v217
	ds_write_b32 v246, v216 offset:1024
	v_max_f32_e32 v224, 0, v224
	v_max_f32_e32 v225, 0, v225
	v_pk_mul_f32 v[224:225], v[224:225], v[162:163]
	v_max_f32_e32 v226, 0, v226
	v_max_f32_e32 v227, 0, v227
	v_pk_fma_f32 v[224:225], v[226:227], v[164:165], v[224:225]
	v_max_f32_e32 v228, 0, v228
	v_max_f32_e32 v229, 0, v229
	v_pk_fma_f32 v[224:225], v[228:229], v[166:167], v[224:225]
	v_max_f32_e32 v230, 0, v230
	v_max_f32_e32 v231, 0, v231
	v_pk_fma_f32 v[224:225], v[230:231], v[168:169], v[224:225]
	v_add_f32_e32 v224, v224, v225
	ds_write_b32 v99, v224 offset:1088
	v_max_f32_e32 v232, 0, v232
	v_max_f32_e32 v233, 0, v233
	v_pk_mul_f32 v[232:233], v[232:233], v[170:171]
	v_max_f32_e32 v234, 0, v234
	v_max_f32_e32 v235, 0, v235
	v_pk_fma_f32 v[232:233], v[234:235], v[172:173], v[232:233]
	v_max_f32_e32 v236, 0, v236
	v_max_f32_e32 v237, 0, v237
	v_pk_fma_f32 v[232:233], v[236:237], v[174:175], v[232:233]
	v_max_f32_e32 v238, 0, v238
	v_max_f32_e32 v239, 0, v239
	v_pk_fma_f32 v[232:233], v[238:239], v[176:177], v[232:233]
	v_add_f32_e32 v232, v232, v233
	ds_write_b32 v246, v232 offset:1088
.LBB0_822:
	s_add_i32 s57, s8, -1
	s_min_i32 s57, s57, s7
	s_lshl_b32 s98, s57, 15
	s_waitcnt vmcnt(12)
	v_lshl_add_u64 v[44:45], v[244:245], 0, s[98:99]
	global_load_dwordx4 v[72:75], v[44:45], off
	global_load_dwordx4 v[76:79], v[44:45], off offset:1024
	global_load_dwordx4 v[40:43], v[44:45], off offset:2048
	s_nop 0
	global_load_dwordx4 v[44:47], v[44:45], off offset:3072
	s_add_i32 s57, s8, -4
	s_cmp_ge_i32 s57, s6
	s_cbranch_scc1 .LBB0_824
	s_waitcnt vmcnt(15)
	ds_write_b128 v103, v[80:83]
	s_waitcnt vmcnt(14)
	ds_write_b128 v103, v[84:87] offset:1152
	ds_read_b128 v[80:83], v107
	ds_read_b128 v[84:87], v107 offset:64
	s_waitcnt vmcnt(13)
	ds_write_b128 v103, v[48:51]
	s_waitcnt vmcnt(12)
	ds_write_b128 v103, v[52:55] offset:1152
	ds_read_b128 v[48:51], v107
	ds_read_b128 v[52:55], v107 offset:64
	s_waitcnt lgkmcnt(4)
	v_mfma_f32_16x16x32_bf16 v[208:211], v[0:3], v[80:83], 0
	v_mfma_f32_16x16x32_bf16 v[212:215], v[8:11], v[80:83], 0
	v_mfma_f32_16x16x32_bf16 v[216:219], v[16:19], v[80:83], 0
	v_mfma_f32_16x16x32_bf16 v[220:223], v[24:27], v[80:83], 0
	v_mfma_f32_16x16x32_bf16 v[208:211], v[4:7], v[84:87], v[208:211]
	v_mfma_f32_16x16x32_bf16 v[212:215], v[12:15], v[84:87], v[212:215]
	v_mfma_f32_16x16x32_bf16 v[216:219], v[20:23], v[84:87], v[216:219]
	v_mfma_f32_16x16x32_bf16 v[220:223], v[28:31], v[84:87], v[220:223]
	s_waitcnt lgkmcnt(0)
	v_mfma_f32_16x16x32_bf16 v[224:227], v[0:3], v[48:51], 0
	v_mfma_f32_16x16x32_bf16 v[228:231], v[8:11], v[48:51], 0
	v_mfma_f32_16x16x32_bf16 v[232:235], v[16:19], v[48:51], 0
	v_mfma_f32_16x16x32_bf16 v[236:239], v[24:27], v[48:51], 0
	v_max_f32_e32 v208, 0, v208
	v_max_f32_e32 v209, 0, v209
	v_pk_mul_f32 v[208:209], v[208:209], v[162:163]
	v_max_f32_e32 v210, 0, v210
	v_max_f32_e32 v211, 0, v211
	v_pk_fma_f32 v[208:209], v[210:211], v[164:165], v[208:209]
	v_mfma_f32_16x16x32_bf16 v[224:227], v[4:7], v[52:55], v[224:227]
	v_max_f32_e32 v212, 0, v212
	v_max_f32_e32 v213, 0, v213
	v_pk_fma_f32 v[208:209], v[212:213], v[166:167], v[208:209]
	v_max_f32_e32 v214, 0, v214
	v_max_f32_e32 v215, 0, v215
	v_pk_fma_f32 v[208:209], v[214:215], v[168:169], v[208:209]
	v_mfma_f32_16x16x32_bf16 v[228:231], v[12:15], v[52:55], v[228:231]
	v_add_f32_e32 v208, v208, v209
	ds_write_b32 v99, v208 offset:2048
	v_max_f32_e32 v216, 0, v216
	v_max_f32_e32 v217, 0, v217
	v_pk_mul_f32 v[216:217], v[216:217], v[170:171]
	v_max_f32_e32 v218, 0, v218
	v_max_f32_e32 v219, 0, v219
	v_mfma_f32_16x16x32_bf16 v[232:235], v[20:23], v[52:55], v[232:235]
	v_pk_fma_f32 v[216:217], v[218:219], v[172:173], v[216:217]
	v_max_f32_e32 v220, 0, v220
	v_max_f32_e32 v221, 0, v221
	v_pk_fma_f32 v[216:217], v[220:221], v[174:175], v[216:217]
	v_max_f32_e32 v222, 0, v222
	v_max_f32_e32 v223, 0, v223
	v_mfma_f32_16x16x32_bf16 v[236:239], v[28:31], v[52:55], v[236:239]
	v_pk_fma_f32 v[216:217], v[222:223], v[176:177], v[216:217]
	v_add_f32_e32 v216, v216, v217
	ds_write_b32 v246, v216 offset:2048
	v_max_f32_e32 v224, 0, v224
	v_max_f32_e32 v225, 0, v225
	v_pk_mul_f32 v[224:225], v[224:225], v[162:163]
	v_max_f32_e32 v226, 0, v226
	v_max_f32_e32 v227, 0, v227
	v_pk_fma_f32 v[224:225], v[226:227], v[164:165], v[224:225]
	v_max_f32_e32 v228, 0, v228
	v_max_f32_e32 v229, 0, v229
	v_pk_fma_f32 v[224:225], v[228:229], v[166:167], v[224:225]
	v_max_f32_e32 v230, 0, v230
	v_max_f32_e32 v231, 0, v231
	v_pk_fma_f32 v[224:225], v[230:231], v[168:169], v[224:225]
	v_add_f32_e32 v224, v224, v225
	ds_write_b32 v99, v224 offset:2112
	v_max_f32_e32 v232, 0, v232
	v_max_f32_e32 v233, 0, v233
	v_pk_mul_f32 v[232:233], v[232:233], v[170:171]
	v_max_f32_e32 v234, 0, v234
	v_max_f32_e32 v235, 0, v235
	v_pk_fma_f32 v[232:233], v[234:235], v[172:173], v[232:233]
	v_max_f32_e32 v236, 0, v236
	v_max_f32_e32 v237, 0, v237
	v_pk_fma_f32 v[232:233], v[236:237], v[174:175], v[232:233]
	v_max_f32_e32 v238, 0, v238
	v_max_f32_e32 v239, 0, v239
	v_pk_fma_f32 v[232:233], v[238:239], v[176:177], v[232:233]
	v_add_f32_e32 v232, v232, v233
	ds_write_b32 v246, v232 offset:2112
.LBB0_824:
	s_min_i32 s57, s8, s7
	s_lshl_b32 s98, s57, 15
	s_cmp_ge_i32 s40, s6
	s_waitcnt vmcnt(12)
	v_lshl_add_u64 v[52:53], v[244:245], 0, s[98:99]
	global_load_dwordx4 v[80:83], v[52:53], off
	global_load_dwordx4 v[84:87], v[52:53], off offset:1024
	global_load_dwordx4 v[48:51], v[52:53], off offset:2048
	s_nop 0
	global_load_dwordx4 v[52:55], v[52:53], off offset:3072
	s_cbranch_scc1 .LBB0_819
	s_waitcnt vmcnt(15)
	ds_write_b128 v103, v[88:91]
	s_waitcnt vmcnt(14)
	ds_write_b128 v103, v[92:95] offset:1152
	ds_read_b128 v[88:91], v107
	ds_read_b128 v[92:95], v107 offset:64
	s_waitcnt vmcnt(13)
	ds_write_b128 v103, v[56:59]
	s_waitcnt vmcnt(12)
	ds_write_b128 v103, v[60:63] offset:1152
	ds_read_b128 v[56:59], v107
	ds_read_b128 v[60:63], v107 offset:64
	s_waitcnt lgkmcnt(4)
	v_mfma_f32_16x16x32_bf16 v[208:211], v[0:3], v[88:91], 0
	v_mfma_f32_16x16x32_bf16 v[212:215], v[8:11], v[88:91], 0
	v_mfma_f32_16x16x32_bf16 v[216:219], v[16:19], v[88:91], 0
	v_mfma_f32_16x16x32_bf16 v[220:223], v[24:27], v[88:91], 0
	v_mfma_f32_16x16x32_bf16 v[208:211], v[4:7], v[92:95], v[208:211]
	v_mfma_f32_16x16x32_bf16 v[212:215], v[12:15], v[92:95], v[212:215]
	v_mfma_f32_16x16x32_bf16 v[216:219], v[20:23], v[92:95], v[216:219]
	v_mfma_f32_16x16x32_bf16 v[220:223], v[28:31], v[92:95], v[220:223]
	s_waitcnt lgkmcnt(0)
	v_mfma_f32_16x16x32_bf16 v[224:227], v[0:3], v[56:59], 0
	v_mfma_f32_16x16x32_bf16 v[228:231], v[8:11], v[56:59], 0
	v_mfma_f32_16x16x32_bf16 v[232:235], v[16:19], v[56:59], 0
	v_mfma_f32_16x16x32_bf16 v[236:239], v[24:27], v[56:59], 0
	v_max_f32_e32 v208, 0, v208
	v_max_f32_e32 v209, 0, v209
	v_pk_mul_f32 v[208:209], v[208:209], v[162:163]
	v_max_f32_e32 v210, 0, v210
	v_max_f32_e32 v211, 0, v211
	v_pk_fma_f32 v[208:209], v[210:211], v[164:165], v[208:209]
	v_mfma_f32_16x16x32_bf16 v[224:227], v[4:7], v[60:63], v[224:227]
	v_max_f32_e32 v212, 0, v212
	v_max_f32_e32 v213, 0, v213
	v_pk_fma_f32 v[208:209], v[212:213], v[166:167], v[208:209]
	v_max_f32_e32 v214, 0, v214
	v_max_f32_e32 v215, 0, v215
	v_pk_fma_f32 v[208:209], v[214:215], v[168:169], v[208:209]
	v_mfma_f32_16x16x32_bf16 v[228:231], v[12:15], v[60:63], v[228:231]
	v_add_f32_e32 v208, v208, v209
	ds_write_b32 v99, v208 offset:3072
	v_max_f32_e32 v216, 0, v216
	v_max_f32_e32 v217, 0, v217
	v_pk_mul_f32 v[216:217], v[216:217], v[170:171]
	v_max_f32_e32 v218, 0, v218
	v_max_f32_e32 v219, 0, v219
	v_mfma_f32_16x16x32_bf16 v[232:235], v[20:23], v[60:63], v[232:235]
	v_pk_fma_f32 v[216:217], v[218:219], v[172:173], v[216:217]
	v_max_f32_e32 v220, 0, v220
	v_max_f32_e32 v221, 0, v221
	v_pk_fma_f32 v[216:217], v[220:221], v[174:175], v[216:217]
	v_max_f32_e32 v222, 0, v222
	v_max_f32_e32 v223, 0, v223
	v_mfma_f32_16x16x32_bf16 v[236:239], v[28:31], v[60:63], v[236:239]
	v_pk_fma_f32 v[216:217], v[222:223], v[176:177], v[216:217]
	v_add_f32_e32 v216, v216, v217
	ds_write_b32 v246, v216 offset:3072
	v_max_f32_e32 v224, 0, v224
	v_max_f32_e32 v225, 0, v225
	v_pk_mul_f32 v[224:225], v[224:225], v[162:163]
	v_max_f32_e32 v226, 0, v226
	v_max_f32_e32 v227, 0, v227
	v_pk_fma_f32 v[224:225], v[226:227], v[164:165], v[224:225]
	v_max_f32_e32 v228, 0, v228
	v_max_f32_e32 v229, 0, v229
	v_pk_fma_f32 v[224:225], v[228:229], v[166:167], v[224:225]
	v_max_f32_e32 v230, 0, v230
	v_max_f32_e32 v231, 0, v231
	v_pk_fma_f32 v[224:225], v[230:231], v[168:169], v[224:225]
	v_add_f32_e32 v224, v224, v225
	ds_write_b32 v99, v224 offset:3136
	v_max_f32_e32 v232, 0, v232
	v_max_f32_e32 v233, 0, v233
	v_pk_mul_f32 v[232:233], v[232:233], v[170:171]
	v_max_f32_e32 v234, 0, v234
	v_max_f32_e32 v235, 0, v235
	v_pk_fma_f32 v[232:233], v[234:235], v[172:173], v[232:233]
	v_max_f32_e32 v236, 0, v236
	v_max_f32_e32 v237, 0, v237
	v_pk_fma_f32 v[232:233], v[236:237], v[174:175], v[232:233]
	v_max_f32_e32 v238, 0, v238
	v_max_f32_e32 v239, 0, v239
	v_pk_fma_f32 v[232:233], v[238:239], v[176:177], v[232:233]
	v_add_f32_e32 v232, v232, v233
	ds_write_b32 v246, v232 offset:3136
	s_branch .LBB0_819

.LBB0_834:
	s_add_i32 s40, s8, -3
	s_min_i32 s9, s40, s7
	s_lshl_b32 s98, s9, 15
	s_waitcnt vmcnt(12)
	v_lshl_add_u64 v[60:61], v[244:245], 0, s[98:99]
	global_load_dwordx4 v[88:91], v[60:61], off
	global_load_dwordx4 v[92:95], v[60:61], off offset:1024
	global_load_dwordx4 v[56:59], v[60:61], off offset:2048
	s_nop 0
	global_load_dwordx4 v[60:63], v[60:61], off offset:3072
	v_add_u32_e32 v103, v178, v98
	s_waitcnt vmcnt(15)
	ds_write_b128 v103, v[64:67]
	s_waitcnt vmcnt(14)
	ds_write_b128 v103, v[68:71] offset:1152
	v_add_u32_e32 v191, v179, v96
	ds_read_b128 v[64:67], v191
	ds_read_b128 v[68:71], v191 offset:64
	s_waitcnt vmcnt(13)
	ds_write_b128 v103, v[32:35]
	s_waitcnt vmcnt(12)
	ds_write_b128 v103, v[36:39] offset:1152
	ds_read_b128 v[32:35], v191
	ds_read_b128 v[36:39], v191 offset:64
	s_waitcnt lgkmcnt(4)
	v_mfma_f32_16x16x32_bf16 v[208:211], v[0:3], v[64:67], 0
	v_mfma_f32_16x16x32_bf16 v[212:215], v[8:11], v[64:67], 0
	v_mfma_f32_16x16x32_bf16 v[216:219], v[16:19], v[64:67], 0
	v_mfma_f32_16x16x32_bf16 v[220:223], v[24:27], v[64:67], 0
	v_mfma_f32_16x16x32_bf16 v[208:211], v[4:7], v[68:71], v[208:211]
	v_mfma_f32_16x16x32_bf16 v[212:215], v[12:15], v[68:71], v[212:215]
	v_mfma_f32_16x16x32_bf16 v[216:219], v[20:23], v[68:71], v[216:219]
	v_mfma_f32_16x16x32_bf16 v[220:223], v[28:31], v[68:71], v[220:223]
	s_waitcnt lgkmcnt(0)
	v_mfma_f32_16x16x32_bf16 v[224:227], v[0:3], v[32:35], 0
	v_mfma_f32_16x16x32_bf16 v[228:231], v[8:11], v[32:35], 0
	v_mfma_f32_16x16x32_bf16 v[232:235], v[16:19], v[32:35], 0
	v_mfma_f32_16x16x32_bf16 v[236:239], v[24:27], v[32:35], 0
	v_max_f32_e32 v208, 0, v208
	v_max_f32_e32 v209, 0, v209
	v_pk_mul_f32 v[208:209], v[208:209], v[162:163]
	v_max_f32_e32 v210, 0, v210
	v_max_f32_e32 v211, 0, v211
	v_pk_fma_f32 v[208:209], v[210:211], v[164:165], v[208:209]
	v_mfma_f32_16x16x32_bf16 v[224:227], v[4:7], v[36:39], v[224:227]
	v_max_f32_e32 v212, 0, v212
	v_max_f32_e32 v213, 0, v213
	v_pk_fma_f32 v[208:209], v[212:213], v[166:167], v[208:209]
	v_max_f32_e32 v214, 0, v214
	v_max_f32_e32 v215, 0, v215
	v_pk_fma_f32 v[208:209], v[214:215], v[168:169], v[208:209]
	v_mfma_f32_16x16x32_bf16 v[228:231], v[12:15], v[36:39], v[228:231]
	v_add_f32_e32 v208, v208, v209
	ds_write_b32 v180, v208
	v_max_f32_e32 v216, 0, v216
	v_max_f32_e32 v217, 0, v217
	v_pk_mul_f32 v[216:217], v[216:217], v[170:171]
	v_max_f32_e32 v218, 0, v218
	v_max_f32_e32 v219, 0, v219
	v_mfma_f32_16x16x32_bf16 v[232:235], v[20:23], v[36:39], v[232:235]
	v_pk_fma_f32 v[216:217], v[218:219], v[172:173], v[216:217]
	v_max_f32_e32 v220, 0, v220
	v_max_f32_e32 v221, 0, v221
	v_pk_fma_f32 v[216:217], v[220:221], v[174:175], v[216:217]
	v_max_f32_e32 v222, 0, v222
	v_max_f32_e32 v223, 0, v223
	v_mfma_f32_16x16x32_bf16 v[236:239], v[28:31], v[36:39], v[236:239]
	v_pk_fma_f32 v[216:217], v[222:223], v[176:177], v[216:217]
	v_add_f32_e32 v216, v216, v217
	ds_write_b32 v246, v216
	v_max_f32_e32 v224, 0, v224
	v_max_f32_e32 v225, 0, v225
	v_pk_mul_f32 v[224:225], v[224:225], v[162:163]
	v_max_f32_e32 v226, 0, v226
	v_max_f32_e32 v227, 0, v227
	v_pk_fma_f32 v[224:225], v[226:227], v[164:165], v[224:225]
	v_max_f32_e32 v228, 0, v228
	v_max_f32_e32 v229, 0, v229
	v_pk_fma_f32 v[224:225], v[228:229], v[166:167], v[224:225]
	v_max_f32_e32 v230, 0, v230
	v_max_f32_e32 v231, 0, v231
	v_pk_fma_f32 v[224:225], v[230:231], v[168:169], v[224:225]
	v_add_f32_e32 v224, v224, v225
	ds_write_b32 v180, v224 offset:64
	v_max_f32_e32 v232, 0, v232
	v_max_f32_e32 v233, 0, v233
	v_pk_mul_f32 v[232:233], v[232:233], v[170:171]
	v_max_f32_e32 v234, 0, v234
	v_max_f32_e32 v235, 0, v235
	v_pk_fma_f32 v[232:233], v[234:235], v[172:173], v[232:233]
	v_max_f32_e32 v236, 0, v236
	v_max_f32_e32 v237, 0, v237
	v_pk_fma_f32 v[232:233], v[236:237], v[174:175], v[232:233]
	v_max_f32_e32 v238, 0, v238
	v_max_f32_e32 v239, 0, v239
	v_pk_fma_f32 v[232:233], v[238:239], v[176:177], v[232:233]
	v_add_f32_e32 v232, v232, v233
	ds_write_b32 v246, v232 offset:64
	s_add_i32 s9, s8, -2
	s_min_i32 s57, s9, s7
	s_lshl_b32 s98, s57, 15
	v_lshl_add_u64 v[36:37], v[244:245], 0, s[98:99]
	global_load_dwordx4 v[64:67], v[36:37], off
	global_load_dwordx4 v[68:71], v[36:37], off offset:1024
	global_load_dwordx4 v[32:35], v[36:37], off offset:2048
	s_nop 0
	global_load_dwordx4 v[36:39], v[36:37], off offset:3072
	s_add_i32 s57, s8, -5
	s_cmp_ge_i32 s57, s6
	s_cbranch_scc1 .LBB0_836
	s_waitcnt vmcnt(15)
	ds_write_b128 v103, v[72:75]
	s_waitcnt vmcnt(14)
	ds_write_b128 v103, v[76:79] offset:1152
	ds_read_b128 v[72:75], v191
	ds_read_b128 v[76:79], v191 offset:64
	s_waitcnt vmcnt(13)
	ds_write_b128 v103, v[40:43]
	s_waitcnt vmcnt(12)
	ds_write_b128 v103, v[44:47] offset:1152
	ds_read_b128 v[40:43], v191
	ds_read_b128 v[44:47], v191 offset:64
	s_waitcnt lgkmcnt(4)
	v_mfma_f32_16x16x32_bf16 v[208:211], v[0:3], v[72:75], 0
	v_mfma_f32_16x16x32_bf16 v[212:215], v[8:11], v[72:75], 0
	v_mfma_f32_16x16x32_bf16 v[216:219], v[16:19], v[72:75], 0
	v_mfma_f32_16x16x32_bf16 v[220:223], v[24:27], v[72:75], 0
	v_mfma_f32_16x16x32_bf16 v[208:211], v[4:7], v[76:79], v[208:211]
	v_mfma_f32_16x16x32_bf16 v[212:215], v[12:15], v[76:79], v[212:215]
	v_mfma_f32_16x16x32_bf16 v[216:219], v[20:23], v[76:79], v[216:219]
	v_mfma_f32_16x16x32_bf16 v[220:223], v[28:31], v[76:79], v[220:223]
	s_waitcnt lgkmcnt(0)
	v_mfma_f32_16x16x32_bf16 v[224:227], v[0:3], v[40:43], 0
	v_mfma_f32_16x16x32_bf16 v[228:231], v[8:11], v[40:43], 0
	v_mfma_f32_16x16x32_bf16 v[232:235], v[16:19], v[40:43], 0
	v_mfma_f32_16x16x32_bf16 v[236:239], v[24:27], v[40:43], 0
	v_max_f32_e32 v208, 0, v208
	v_max_f32_e32 v209, 0, v209
	v_pk_mul_f32 v[208:209], v[208:209], v[162:163]
	v_max_f32_e32 v210, 0, v210
	v_max_f32_e32 v211, 0, v211
	v_pk_fma_f32 v[208:209], v[210:211], v[164:165], v[208:209]
	v_mfma_f32_16x16x32_bf16 v[224:227], v[4:7], v[44:47], v[224:227]
	v_max_f32_e32 v212, 0, v212
	v_max_f32_e32 v213, 0, v213
	v_pk_fma_f32 v[208:209], v[212:213], v[166:167], v[208:209]
	v_max_f32_e32 v214, 0, v214
	v_max_f32_e32 v215, 0, v215
	v_pk_fma_f32 v[208:209], v[214:215], v[168:169], v[208:209]
	v_mfma_f32_16x16x32_bf16 v[228:231], v[12:15], v[44:47], v[228:231]
	v_add_f32_e32 v208, v208, v209
	ds_write_b32 v180, v208 offset:1024
	v_max_f32_e32 v216, 0, v216
	v_max_f32_e32 v217, 0, v217
	v_pk_mul_f32 v[216:217], v[216:217], v[170:171]
	v_max_f32_e32 v218, 0, v218
	v_max_f32_e32 v219, 0, v219
	v_mfma_f32_16x16x32_bf16 v[232:235], v[20:23], v[44:47], v[232:235]
	v_pk_fma_f32 v[216:217], v[218:219], v[172:173], v[216:217]
	v_max_f32_e32 v220, 0, v220
	v_max_f32_e32 v221, 0, v221
	v_pk_fma_f32 v[216:217], v[220:221], v[174:175], v[216:217]
	v_max_f32_e32 v222, 0, v222
	v_max_f32_e32 v223, 0, v223
	v_mfma_f32_16x16x32_bf16 v[236:239], v[28:31], v[44:47], v[236:239]
	v_pk_fma_f32 v[216:217], v[222:223], v[176:177], v[216:217]
	v_add_f32_e32 v216, v216, v217
	ds_write_b32 v246, v216 offset:1024
	v_max_f32_e32 v224, 0, v224
	v_max_f32_e32 v225, 0, v225
	v_pk_mul_f32 v[224:225], v[224:225], v[162:163]
	v_max_f32_e32 v226, 0, v226
	v_max_f32_e32 v227, 0, v227
	v_pk_fma_f32 v[224:225], v[226:227], v[164:165], v[224:225]
	v_max_f32_e32 v228, 0, v228
	v_max_f32_e32 v229, 0, v229
	v_pk_fma_f32 v[224:225], v[228:229], v[166:167], v[224:225]
	v_max_f32_e32 v230, 0, v230
	v_max_f32_e32 v231, 0, v231
	v_pk_fma_f32 v[224:225], v[230:231], v[168:169], v[224:225]
	v_add_f32_e32 v224, v224, v225
	ds_write_b32 v180, v224 offset:1088
	v_max_f32_e32 v232, 0, v232
	v_max_f32_e32 v233, 0, v233
	v_pk_mul_f32 v[232:233], v[232:233], v[170:171]
	v_max_f32_e32 v234, 0, v234
	v_max_f32_e32 v235, 0, v235
	v_pk_fma_f32 v[232:233], v[234:235], v[172:173], v[232:233]
	v_max_f32_e32 v236, 0, v236
	v_max_f32_e32 v237, 0, v237
	v_pk_fma_f32 v[232:233], v[236:237], v[174:175], v[232:233]
	v_max_f32_e32 v238, 0, v238
	v_max_f32_e32 v239, 0, v239
	v_pk_fma_f32 v[232:233], v[238:239], v[176:177], v[232:233]
	v_add_f32_e32 v232, v232, v233
	ds_write_b32 v246, v232 offset:1088
.LBB0_836:
	s_add_i32 s57, s8, -1
	s_min_i32 s57, s57, s7
	s_lshl_b32 s98, s57, 15
	s_waitcnt vmcnt(12)
	v_lshl_add_u64 v[44:45], v[244:245], 0, s[98:99]
	global_load_dwordx4 v[72:75], v[44:45], off
	global_load_dwordx4 v[76:79], v[44:45], off offset:1024
	global_load_dwordx4 v[40:43], v[44:45], off offset:2048
	s_nop 0
	global_load_dwordx4 v[44:47], v[44:45], off offset:3072
	s_add_i32 s57, s8, -4
	s_cmp_ge_i32 s57, s6
	s_cbranch_scc1 .LBB0_838
	s_waitcnt vmcnt(15)
	ds_write_b128 v103, v[80:83]
	s_waitcnt vmcnt(14)
	ds_write_b128 v103, v[84:87] offset:1152
	ds_read_b128 v[80:83], v191
	ds_read_b128 v[84:87], v191 offset:64
	s_waitcnt vmcnt(13)
	ds_write_b128 v103, v[48:51]
	s_waitcnt vmcnt(12)
	ds_write_b128 v103, v[52:55] offset:1152
	ds_read_b128 v[48:51], v191
	ds_read_b128 v[52:55], v191 offset:64
	s_waitcnt lgkmcnt(4)
	v_mfma_f32_16x16x32_bf16 v[208:211], v[0:3], v[80:83], 0
	v_mfma_f32_16x16x32_bf16 v[212:215], v[8:11], v[80:83], 0
	v_mfma_f32_16x16x32_bf16 v[216:219], v[16:19], v[80:83], 0
	v_mfma_f32_16x16x32_bf16 v[220:223], v[24:27], v[80:83], 0
	v_mfma_f32_16x16x32_bf16 v[208:211], v[4:7], v[84:87], v[208:211]
	v_mfma_f32_16x16x32_bf16 v[212:215], v[12:15], v[84:87], v[212:215]
	v_mfma_f32_16x16x32_bf16 v[216:219], v[20:23], v[84:87], v[216:219]
	v_mfma_f32_16x16x32_bf16 v[220:223], v[28:31], v[84:87], v[220:223]
	s_waitcnt lgkmcnt(0)
	v_mfma_f32_16x16x32_bf16 v[224:227], v[0:3], v[48:51], 0
	v_mfma_f32_16x16x32_bf16 v[228:231], v[8:11], v[48:51], 0
	v_mfma_f32_16x16x32_bf16 v[232:235], v[16:19], v[48:51], 0
	v_mfma_f32_16x16x32_bf16 v[236:239], v[24:27], v[48:51], 0
	v_max_f32_e32 v208, 0, v208
	v_max_f32_e32 v209, 0, v209
	v_pk_mul_f32 v[208:209], v[208:209], v[162:163]
	v_max_f32_e32 v210, 0, v210
	v_max_f32_e32 v211, 0, v211
	v_pk_fma_f32 v[208:209], v[210:211], v[164:165], v[208:209]
	v_mfma_f32_16x16x32_bf16 v[224:227], v[4:7], v[52:55], v[224:227]
	v_max_f32_e32 v212, 0, v212
	v_max_f32_e32 v213, 0, v213
	v_pk_fma_f32 v[208:209], v[212:213], v[166:167], v[208:209]
	v_max_f32_e32 v214, 0, v214
	v_max_f32_e32 v215, 0, v215
	v_pk_fma_f32 v[208:209], v[214:215], v[168:169], v[208:209]
	v_mfma_f32_16x16x32_bf16 v[228:231], v[12:15], v[52:55], v[228:231]
	v_add_f32_e32 v208, v208, v209
	ds_write_b32 v180, v208 offset:2048
	v_max_f32_e32 v216, 0, v216
	v_max_f32_e32 v217, 0, v217
	v_pk_mul_f32 v[216:217], v[216:217], v[170:171]
	v_max_f32_e32 v218, 0, v218
	v_max_f32_e32 v219, 0, v219
	v_mfma_f32_16x16x32_bf16 v[232:235], v[20:23], v[52:55], v[232:235]
	v_pk_fma_f32 v[216:217], v[218:219], v[172:173], v[216:217]
	v_max_f32_e32 v220, 0, v220
	v_max_f32_e32 v221, 0, v221
	v_pk_fma_f32 v[216:217], v[220:221], v[174:175], v[216:217]
	v_max_f32_e32 v222, 0, v222
	v_max_f32_e32 v223, 0, v223
	v_mfma_f32_16x16x32_bf16 v[236:239], v[28:31], v[52:55], v[236:239]
	v_pk_fma_f32 v[216:217], v[222:223], v[176:177], v[216:217]
	v_add_f32_e32 v216, v216, v217
	ds_write_b32 v246, v216 offset:2048
	v_max_f32_e32 v224, 0, v224
	v_max_f32_e32 v225, 0, v225
	v_pk_mul_f32 v[224:225], v[224:225], v[162:163]
	v_max_f32_e32 v226, 0, v226
	v_max_f32_e32 v227, 0, v227
	v_pk_fma_f32 v[224:225], v[226:227], v[164:165], v[224:225]
	v_max_f32_e32 v228, 0, v228
	v_max_f32_e32 v229, 0, v229
	v_pk_fma_f32 v[224:225], v[228:229], v[166:167], v[224:225]
	v_max_f32_e32 v230, 0, v230
	v_max_f32_e32 v231, 0, v231
	v_pk_fma_f32 v[224:225], v[230:231], v[168:169], v[224:225]
	v_add_f32_e32 v224, v224, v225
	ds_write_b32 v180, v224 offset:2112
	v_max_f32_e32 v232, 0, v232
	v_max_f32_e32 v233, 0, v233
	v_pk_mul_f32 v[232:233], v[232:233], v[170:171]
	v_max_f32_e32 v234, 0, v234
	v_max_f32_e32 v235, 0, v235
	v_pk_fma_f32 v[232:233], v[234:235], v[172:173], v[232:233]
	v_max_f32_e32 v236, 0, v236
	v_max_f32_e32 v237, 0, v237
	v_pk_fma_f32 v[232:233], v[236:237], v[174:175], v[232:233]
	v_max_f32_e32 v238, 0, v238
	v_max_f32_e32 v239, 0, v239
	v_pk_fma_f32 v[232:233], v[238:239], v[176:177], v[232:233]
	v_add_f32_e32 v232, v232, v233
	ds_write_b32 v246, v232 offset:2112
.LBB0_838:
	s_min_i32 s57, s8, s7
	s_lshl_b32 s98, s57, 15
	s_cmp_ge_i32 s40, s6
	s_waitcnt vmcnt(12)
	v_lshl_add_u64 v[52:53], v[244:245], 0, s[98:99]
	global_load_dwordx4 v[80:83], v[52:53], off
	global_load_dwordx4 v[84:87], v[52:53], off offset:1024
	global_load_dwordx4 v[48:51], v[52:53], off offset:2048
	s_nop 0
	global_load_dwordx4 v[52:55], v[52:53], off offset:3072
	s_cbranch_scc1 .LBB0_833
	s_waitcnt vmcnt(15)
	ds_write_b128 v103, v[88:91]
	s_waitcnt vmcnt(14)
	ds_write_b128 v103, v[92:95] offset:1152
	ds_read_b128 v[88:91], v191
	ds_read_b128 v[92:95], v191 offset:64
	s_waitcnt vmcnt(13)
	ds_write_b128 v103, v[56:59]
	s_waitcnt vmcnt(12)
	ds_write_b128 v103, v[60:63] offset:1152
	ds_read_b128 v[56:59], v191
	ds_read_b128 v[60:63], v191 offset:64
	s_waitcnt lgkmcnt(4)
	v_mfma_f32_16x16x32_bf16 v[208:211], v[0:3], v[88:91], 0
	v_mfma_f32_16x16x32_bf16 v[212:215], v[8:11], v[88:91], 0
	v_mfma_f32_16x16x32_bf16 v[216:219], v[16:19], v[88:91], 0
	v_mfma_f32_16x16x32_bf16 v[220:223], v[24:27], v[88:91], 0
	v_mfma_f32_16x16x32_bf16 v[208:211], v[4:7], v[92:95], v[208:211]
	v_mfma_f32_16x16x32_bf16 v[212:215], v[12:15], v[92:95], v[212:215]
	v_mfma_f32_16x16x32_bf16 v[216:219], v[20:23], v[92:95], v[216:219]
	v_mfma_f32_16x16x32_bf16 v[220:223], v[28:31], v[92:95], v[220:223]
	s_waitcnt lgkmcnt(0)
	v_mfma_f32_16x16x32_bf16 v[224:227], v[0:3], v[56:59], 0
	v_mfma_f32_16x16x32_bf16 v[228:231], v[8:11], v[56:59], 0
	v_mfma_f32_16x16x32_bf16 v[232:235], v[16:19], v[56:59], 0
	v_mfma_f32_16x16x32_bf16 v[236:239], v[24:27], v[56:59], 0
	v_max_f32_e32 v208, 0, v208
	v_max_f32_e32 v209, 0, v209
	v_pk_mul_f32 v[208:209], v[208:209], v[162:163]
	v_max_f32_e32 v210, 0, v210
	v_max_f32_e32 v211, 0, v211
	v_pk_fma_f32 v[208:209], v[210:211], v[164:165], v[208:209]
	v_mfma_f32_16x16x32_bf16 v[224:227], v[4:7], v[60:63], v[224:227]
	v_max_f32_e32 v212, 0, v212
	v_max_f32_e32 v213, 0, v213
	v_pk_fma_f32 v[208:209], v[212:213], v[166:167], v[208:209]
	v_max_f32_e32 v214, 0, v214
	v_max_f32_e32 v215, 0, v215
	v_pk_fma_f32 v[208:209], v[214:215], v[168:169], v[208:209]
	v_mfma_f32_16x16x32_bf16 v[228:231], v[12:15], v[60:63], v[228:231]
	v_add_f32_e32 v208, v208, v209
	ds_write_b32 v180, v208 offset:3072
	v_max_f32_e32 v216, 0, v216
	v_max_f32_e32 v217, 0, v217
	v_pk_mul_f32 v[216:217], v[216:217], v[170:171]
	v_max_f32_e32 v218, 0, v218
	v_max_f32_e32 v219, 0, v219
	v_mfma_f32_16x16x32_bf16 v[232:235], v[20:23], v[60:63], v[232:235]
	v_pk_fma_f32 v[216:217], v[218:219], v[172:173], v[216:217]
	v_max_f32_e32 v220, 0, v220
	v_max_f32_e32 v221, 0, v221
	v_pk_fma_f32 v[216:217], v[220:221], v[174:175], v[216:217]
	v_max_f32_e32 v222, 0, v222
	v_max_f32_e32 v223, 0, v223
	v_mfma_f32_16x16x32_bf16 v[236:239], v[28:31], v[60:63], v[236:239]
	v_pk_fma_f32 v[216:217], v[222:223], v[176:177], v[216:217]
	v_add_f32_e32 v216, v216, v217
	ds_write_b32 v246, v216 offset:3072
	v_max_f32_e32 v224, 0, v224
	v_max_f32_e32 v225, 0, v225
	v_pk_mul_f32 v[224:225], v[224:225], v[162:163]
	v_max_f32_e32 v226, 0, v226
	v_max_f32_e32 v227, 0, v227
	v_pk_fma_f32 v[224:225], v[226:227], v[164:165], v[224:225]
	v_max_f32_e32 v228, 0, v228
	v_max_f32_e32 v229, 0, v229
	v_pk_fma_f32 v[224:225], v[228:229], v[166:167], v[224:225]
	v_max_f32_e32 v230, 0, v230
	v_max_f32_e32 v231, 0, v231
	v_pk_fma_f32 v[224:225], v[230:231], v[168:169], v[224:225]
	v_add_f32_e32 v224, v224, v225
	ds_write_b32 v180, v224 offset:3136
	v_max_f32_e32 v232, 0, v232
	v_max_f32_e32 v233, 0, v233
	v_pk_mul_f32 v[232:233], v[232:233], v[170:171]
	v_max_f32_e32 v234, 0, v234
	v_max_f32_e32 v235, 0, v235
	v_pk_fma_f32 v[232:233], v[234:235], v[172:173], v[232:233]
	v_max_f32_e32 v236, 0, v236
	v_max_f32_e32 v237, 0, v237
	v_pk_fma_f32 v[232:233], v[236:237], v[174:175], v[232:233]
	v_max_f32_e32 v238, 0, v238
	v_max_f32_e32 v239, 0, v239
	v_pk_fma_f32 v[232:233], v[238:239], v[176:177], v[232:233]
	v_add_f32_e32 v232, v232, v233
	ds_write_b32 v246, v232 offset:3136
	s_branch .LBB0_833
